# MLA main loops rescale running O and l only when a tile raises a row max by more than 8 log2 units (deferred rescale, f32 statistics unchanged)
# speedup vs baseline: 1.0070x; 1.0070x over previous
; DI float fexp2(float x) { return __builtin_amdgcn_exp2f(x); }
; template <bool ATOM>
; DI void mla_unit(LAS unsigned char* lds, const AttnPtrs& P, int b, int hd, int qb) {
;     ...
;             float mloc = x0[0];
; #pragma unroll
;             for (int i = 1; i < 16; ++i) mloc = fmaxf(mloc, x0[i]);
;             mloc = fmaxf(mloc, __shfl_xor(mloc, 32));
;             const float mnew = fmaxf(mrun, mloc);
;             const float msafe = mnew == -INFINITY ? 0.f : mnew;
;             const float alpha = fexp2(mrun - msafe);
;             float psum = 0.f;
; #pragma unroll
;             for (int i = 0; i < 16; ++i) { x0[i] = fexp2(x0[i] - msafe); psum += x0[i]; }
;             lrun = lrun * alpha + psum; mrun = mnew;
;             if (__builtin_amdgcn_ballot_w64(alpha != 1.f) != 0ull) {
; #pragma unroll
;                 for (int d = 0; d < NDV; ++d)
; #pragma unroll
;                     for (int i = 0; i < 16; ++i) o[d][i] *= alpha;
;             }
.LBB0_1054:
	v_max_f32_e32 v0, v81, v81
	v_max_f32_e32 v1, v80, v80
	v_max_f32_e32 v0, v1, v0
	v_max3_f32 v0, v0, v2, v3
	v_max3_f32 v0, v0, v4, v5
	v_mbcnt_hi_u32_b32 v1, -1, v189
	v_max3_f32 v0, v0, v6, v7
	v_and_b32_e32 v83, 64, v1
	v_max3_f32 v0, v0, v8, v9
	v_xor_b32_e32 v82, 32, v1
	v_add_u32_e32 v83, 64, v83
	v_max3_f32 v0, v0, v10, v11
	v_cmp_lt_i32_e32 vcc, v82, v83
	v_max3_f32 v0, v0, v12, v13
	v_max3_f32 v0, v0, v14, v15
	v_cndmask_b32_e32 v1, v1, v82, vcc
	v_lshlrev_b32_e32 v1, 2, v1
	ds_bpermute_b32 v1, v1, v0
	s_waitcnt lgkmcnt(0)
	v_max3_f32 v212, v124, v0, v1
	v_add_f32_e32 v191, 0x41000000, v124
	v_cmp_gt_f32_e32 vcc, v212, v191
	s_cbranch_vccnz .Lmla_upd_1
	v_cmp_neq_f32_e32 vcc, s5, v124
	v_mov_b32_e32 v212, v124
	v_mov_b32_e32 v0, 1.0
	v_cndmask_b32_e32 v1, 0, v124, vcc
	s_branch .LBB0_1056
.Lmla_upd_1:
	v_cmp_neq_f32_e32 vcc, s5, v212
	s_nop 1
	v_cndmask_b32_e32 v1, 0, v212, vcc
	v_sub_f32_e32 v0, v124, v1
	v_exp_f32_e32 v0, v0
	s_nop 0
	v_cmp_neq_f32_e32 vcc, 1.0, v0
	s_cbranch_vccz .LBB0_1056
	v_pk_mul_f32 v[78:79], v[78:79], v[0:1] op_sel_hi:[1,0]
	v_pk_mul_f32 v[76:77], v[76:77], v[0:1] op_sel_hi:[1,0]
	v_pk_mul_f32 v[74:75], v[74:75], v[0:1] op_sel_hi:[1,0]
	v_pk_mul_f32 v[72:73], v[72:73], v[0:1] op_sel_hi:[1,0]
	v_pk_mul_f32 v[70:71], v[70:71], v[0:1] op_sel_hi:[1,0]
	v_pk_mul_f32 v[68:69], v[68:69], v[0:1] op_sel_hi:[1,0]
	v_pk_mul_f32 v[66:67], v[66:67], v[0:1] op_sel_hi:[1,0]
	v_pk_mul_f32 v[64:65], v[64:65], v[0:1] op_sel_hi:[1,0]
	v_pk_mul_f32 v[62:63], v[62:63], v[0:1] op_sel_hi:[1,0]
	v_pk_mul_f32 v[60:61], v[60:61], v[0:1] op_sel_hi:[1,0]
	v_pk_mul_f32 v[58:59], v[58:59], v[0:1] op_sel_hi:[1,0]
	v_pk_mul_f32 v[56:57], v[56:57], v[0:1] op_sel_hi:[1,0]
	v_pk_mul_f32 v[54:55], v[54:55], v[0:1] op_sel_hi:[1,0]
	v_pk_mul_f32 v[52:53], v[52:53], v[0:1] op_sel_hi:[1,0]
	v_pk_mul_f32 v[50:51], v[50:51], v[0:1] op_sel_hi:[1,0]
	v_pk_mul_f32 v[48:49], v[48:49], v[0:1] op_sel_hi:[1,0]
	v_pk_mul_f32 v[46:47], v[46:47], v[0:1] op_sel_hi:[1,0]
	v_pk_mul_f32 v[44:45], v[44:45], v[0:1] op_sel_hi:[1,0]
	v_pk_mul_f32 v[42:43], v[42:43], v[0:1] op_sel_hi:[1,0]
	v_pk_mul_f32 v[40:41], v[40:41], v[0:1] op_sel_hi:[1,0]
	v_pk_mul_f32 v[38:39], v[38:39], v[0:1] op_sel_hi:[1,0]
	v_pk_mul_f32 v[36:37], v[36:37], v[0:1] op_sel_hi:[1,0]
	v_pk_mul_f32 v[34:35], v[34:35], v[0:1] op_sel_hi:[1,0]
	v_pk_mul_f32 v[32:33], v[32:33], v[0:1] op_sel_hi:[1,0]
	v_pk_mul_f32 v[30:31], v[30:31], v[0:1] op_sel_hi:[1,0]
	v_pk_mul_f32 v[28:29], v[28:29], v[0:1] op_sel_hi:[1,0]
	v_pk_mul_f32 v[26:27], v[26:27], v[0:1] op_sel_hi:[1,0]
	v_pk_mul_f32 v[24:25], v[24:25], v[0:1] op_sel_hi:[1,0]
	v_pk_mul_f32 v[22:23], v[22:23], v[0:1] op_sel_hi:[1,0]
	v_pk_mul_f32 v[20:21], v[20:21], v[0:1] op_sel_hi:[1,0]
	v_pk_mul_f32 v[18:19], v[18:19], v[0:1] op_sel_hi:[1,0]
	v_pk_mul_f32 v[16:17], v[16:17], v[0:1] op_sel_hi:[1,0]
